# v4 + SwiGLU-out residual epilogue: gate loaded once per tile, residual row groups double-buffered, scalar fma
# baseline (speedup 1.0000x reference)
.LBB0_1206:
	s_lshl_b32 s16, s46, 8
	s_add_i32 s16, s16, s36
	s_ashr_i32 s17, s16, 13
	s_mul_i32 s18, s17, 0x1800
	s_ashr_i32 s19, s18, 31
	v_lshl_or_b32 v144, s47, 8, v152
	s_lshl_b64 s[18:19], s[18:19], 2
	v_ashrrev_i32_e32 v145, 31, v144
	s_add_u32 s18, s29, s18
	s_addc_u32 s19, s35, s19
	v_lshlrev_b64 v[144:145], 2, v[144:145]
	v_lshl_add_u64 v[146:147], s[18:19], 0, v[144:145]
	global_load_dwordx4 v[156:159], v[146:147], off
	global_load_dwordx4 v[168:171], v[146:147], off offset:16
	global_load_dwordx4 v[172:175], v[146:147], off offset:512
	global_load_dwordx4 v[184:187], v[146:147], off offset:528
	v_or_b32_e32 v148, s16, v150
	v_ashrrev_i32_e32 v149, 31, v148
	v_lshlrev_b64 v[188:189], 12, v[148:149]
	v_lshl_add_u64 v[188:189], s[30:31], 0, v[188:189]
	v_lshl_add_u64 v[188:189], v[188:189], 0, v[144:145]
	global_load_dwordx4 v[160:163], v[188:189], off
	global_load_dwordx4 v[164:167], v[188:189], off offset:16
	global_load_dwordx4 v[176:179], v[188:189], off offset:512
	global_load_dwordx4 v[180:183], v[188:189], off offset:528
	v_or_b32_e32 v148, s16, v150
	v_or_b32_e32 v148, 16, v148
	v_ashrrev_i32_e32 v149, 31, v148
	v_lshlrev_b64 v[190:191], 12, v[148:149]
	v_lshl_add_u64 v[190:191], s[30:31], 0, v[190:191]
	v_lshl_add_u64 v[190:191], v[190:191], 0, v[144:145]
	global_load_dwordx4 v[224:227], v[190:191], off
	global_load_dwordx4 v[228:231], v[190:191], off offset:16
	global_load_dwordx4 v[232:235], v[190:191], off offset:512
	global_load_dwordx4 v[236:239], v[190:191], off offset:528
	v_or_b32_e32 v148, s16, v150
	v_or_b32_e32 v148, 32, v148
	v_ashrrev_i32_e32 v149, 31, v148
	v_lshlrev_b64 v[240:241], 12, v[148:149]
	v_lshl_add_u64 v[240:241], s[30:31], 0, v[240:241]
	v_lshl_add_u64 v[240:241], v[240:241], 0, v[144:145]
	v_or_b32_e32 v148, s16, v150
	v_or_b32_e32 v148, 48, v148
	v_ashrrev_i32_e32 v149, 31, v148
	v_lshlrev_b64 v[242:243], 12, v[148:149]
	v_lshl_add_u64 v[242:243], s[30:31], 0, v[242:243]
	v_lshl_add_u64 v[242:243], v[242:243], 0, v[144:145]
	s_addk_i32 s16, 0x80
	v_or_b32_e32 v148, s16, v150
	v_ashrrev_i32_e32 v149, 31, v148
	v_lshlrev_b64 v[244:245], 12, v[148:149]
	v_lshl_add_u64 v[244:245], s[30:31], 0, v[244:245]
	v_lshl_add_u64 v[244:245], v[244:245], 0, v[144:145]
	v_or_b32_e32 v148, s16, v150
	v_or_b32_e32 v148, 16, v148
	v_ashrrev_i32_e32 v149, 31, v148
	v_lshlrev_b64 v[246:247], 12, v[148:149]
	v_lshl_add_u64 v[246:247], s[30:31], 0, v[246:247]
	v_lshl_add_u64 v[246:247], v[246:247], 0, v[144:145]
	v_or_b32_e32 v148, s16, v150
	v_or_b32_e32 v148, 32, v148
	v_ashrrev_i32_e32 v149, 31, v148
	v_lshlrev_b64 v[248:249], 12, v[148:149]
	v_lshl_add_u64 v[248:249], s[30:31], 0, v[248:249]
	v_lshl_add_u64 v[248:249], v[248:249], 0, v[144:145]
	v_or_b32_e32 v148, s16, v150
	v_or_b32_e32 v148, 48, v148
	v_ashrrev_i32_e32 v149, 31, v148
	v_lshlrev_b64 v[146:147], 12, v[148:149]
	v_lshl_add_u64 v[146:147], s[30:31], 0, v[146:147]
	v_lshl_add_u64 v[146:147], v[146:147], 0, v[144:145]
	s_waitcnt vmcnt(4)
	v_fma_f32 v124, v124, v156, v160
	v_fma_f32 v125, v125, v157, v161
	v_fma_f32 v126, v126, v158, v162
	v_fma_f32 v127, v127, v159, v163
	v_fma_f32 v120, v120, v168, v164
	v_fma_f32 v121, v121, v169, v165
	v_fma_f32 v122, v122, v170, v166
	v_fma_f32 v123, v123, v171, v167
	v_fma_f32 v116, v116, v172, v176
	v_fma_f32 v117, v117, v173, v177
	v_fma_f32 v118, v118, v174, v178
	v_fma_f32 v119, v119, v175, v179
	v_fma_f32 v112, v112, v184, v180
	v_fma_f32 v113, v113, v185, v181
	v_fma_f32 v114, v114, v186, v182
	v_fma_f32 v115, v115, v187, v183
	global_store_dwordx4 v[188:189], v[124:127], off
	global_store_dwordx4 v[188:189], v[120:123], off offset:16
	global_store_dwordx4 v[188:189], v[116:119], off offset:512
	global_store_dwordx4 v[188:189], v[112:115], off offset:528
	global_load_dwordx4 v[160:163], v[240:241], off
	global_load_dwordx4 v[164:167], v[240:241], off offset:16
	global_load_dwordx4 v[176:179], v[240:241], off offset:512
	global_load_dwordx4 v[180:183], v[240:241], off offset:528
	s_waitcnt vmcnt(8)
	v_fma_f32 v108, v108, v156, v224
	v_fma_f32 v109, v109, v157, v225
	v_fma_f32 v110, v110, v158, v226
	v_fma_f32 v111, v111, v159, v227
	v_fma_f32 v104, v104, v168, v228
	v_fma_f32 v105, v105, v169, v229
	v_fma_f32 v106, v106, v170, v230
	v_fma_f32 v107, v107, v171, v231
	v_fma_f32 v100, v100, v172, v232
	v_fma_f32 v101, v101, v173, v233
	v_fma_f32 v102, v102, v174, v234
	v_fma_f32 v103, v103, v175, v235
	v_fma_f32 v96, v96, v184, v236
	v_fma_f32 v97, v97, v185, v237
	v_fma_f32 v98, v98, v186, v238
	v_fma_f32 v99, v99, v187, v239
	global_store_dwordx4 v[190:191], v[108:111], off
	global_store_dwordx4 v[190:191], v[104:107], off offset:16
	global_store_dwordx4 v[190:191], v[100:103], off offset:512
	global_store_dwordx4 v[190:191], v[96:99], off offset:528
	global_load_dwordx4 v[224:227], v[242:243], off
	global_load_dwordx4 v[228:231], v[242:243], off offset:16
	global_load_dwordx4 v[232:235], v[242:243], off offset:512
	global_load_dwordx4 v[236:239], v[242:243], off offset:528
	s_waitcnt vmcnt(8)
	v_fma_f32 v92, v92, v156, v160
	v_fma_f32 v93, v93, v157, v161
	v_fma_f32 v94, v94, v158, v162
	v_fma_f32 v95, v95, v159, v163
	v_fma_f32 v88, v88, v168, v164
	v_fma_f32 v89, v89, v169, v165
	v_fma_f32 v90, v90, v170, v166
	v_fma_f32 v91, v91, v171, v167
	v_fma_f32 v84, v84, v172, v176
	v_fma_f32 v85, v85, v173, v177
	v_fma_f32 v86, v86, v174, v178
	v_fma_f32 v87, v87, v175, v179
	v_fma_f32 v80, v80, v184, v180
	v_fma_f32 v81, v81, v185, v181
	v_fma_f32 v82, v82, v186, v182
	v_fma_f32 v83, v83, v187, v183
	global_store_dwordx4 v[240:241], v[92:95], off
	global_store_dwordx4 v[240:241], v[88:91], off offset:16
	global_store_dwordx4 v[240:241], v[84:87], off offset:512
	global_store_dwordx4 v[240:241], v[80:83], off offset:528
	global_load_dwordx4 v[160:163], v[244:245], off
	global_load_dwordx4 v[164:167], v[244:245], off offset:16
	global_load_dwordx4 v[176:179], v[244:245], off offset:512
	global_load_dwordx4 v[180:183], v[244:245], off offset:528
	s_waitcnt vmcnt(8)
	v_fma_f32 v76, v76, v156, v224
	v_fma_f32 v77, v77, v157, v225
	v_fma_f32 v78, v78, v158, v226
	v_fma_f32 v79, v79, v159, v227
	v_fma_f32 v72, v72, v168, v228
	v_fma_f32 v73, v73, v169, v229
	v_fma_f32 v74, v74, v170, v230
	v_fma_f32 v75, v75, v171, v231
	v_fma_f32 v68, v68, v172, v232
	v_fma_f32 v69, v69, v173, v233
	v_fma_f32 v70, v70, v174, v234
	v_fma_f32 v71, v71, v175, v235
	v_fma_f32 v64, v64, v184, v236
	v_fma_f32 v65, v65, v185, v237
	v_fma_f32 v66, v66, v186, v238
	v_fma_f32 v67, v67, v187, v239
	global_store_dwordx4 v[242:243], v[76:79], off
	global_store_dwordx4 v[242:243], v[72:75], off offset:16
	global_store_dwordx4 v[242:243], v[68:71], off offset:512
	global_store_dwordx4 v[242:243], v[64:67], off offset:528
	global_load_dwordx4 v[224:227], v[246:247], off
	global_load_dwordx4 v[228:231], v[246:247], off offset:16
	global_load_dwordx4 v[232:235], v[246:247], off offset:512
	global_load_dwordx4 v[236:239], v[246:247], off offset:528
	s_waitcnt vmcnt(8)
	v_fma_f32 v60, v60, v156, v160
	v_fma_f32 v61, v61, v157, v161
	v_fma_f32 v62, v62, v158, v162
	v_fma_f32 v63, v63, v159, v163
	v_fma_f32 v56, v56, v168, v164
	v_fma_f32 v57, v57, v169, v165
	v_fma_f32 v58, v58, v170, v166
	v_fma_f32 v59, v59, v171, v167
	v_fma_f32 v52, v52, v172, v176
	v_fma_f32 v53, v53, v173, v177
	v_fma_f32 v54, v54, v174, v178
	v_fma_f32 v55, v55, v175, v179
	v_fma_f32 v48, v48, v184, v180
	v_fma_f32 v49, v49, v185, v181
	v_fma_f32 v50, v50, v186, v182
	v_fma_f32 v51, v51, v187, v183
	global_store_dwordx4 v[244:245], v[60:63], off
	global_store_dwordx4 v[244:245], v[56:59], off offset:16
	global_store_dwordx4 v[244:245], v[52:55], off offset:512
	global_store_dwordx4 v[244:245], v[48:51], off offset:528
	global_load_dwordx4 v[160:163], v[248:249], off
	global_load_dwordx4 v[164:167], v[248:249], off offset:16
	global_load_dwordx4 v[176:179], v[248:249], off offset:512
	global_load_dwordx4 v[180:183], v[248:249], off offset:528
	s_waitcnt vmcnt(8)
	v_fma_f32 v44, v44, v156, v224
	v_fma_f32 v45, v45, v157, v225
	v_fma_f32 v46, v46, v158, v226
	v_fma_f32 v47, v47, v159, v227
	v_fma_f32 v40, v40, v168, v228
	v_fma_f32 v41, v41, v169, v229
	v_fma_f32 v42, v42, v170, v230
	v_fma_f32 v43, v43, v171, v231
	v_fma_f32 v36, v36, v172, v232
	v_fma_f32 v37, v37, v173, v233
	v_fma_f32 v38, v38, v174, v234
	v_fma_f32 v39, v39, v175, v235
	v_fma_f32 v32, v32, v184, v236
	v_fma_f32 v33, v33, v185, v237
	v_fma_f32 v34, v34, v186, v238
	v_fma_f32 v35, v35, v187, v239
	global_store_dwordx4 v[246:247], v[44:47], off
	global_store_dwordx4 v[246:247], v[40:43], off offset:16
	global_store_dwordx4 v[246:247], v[36:39], off offset:512
	global_store_dwordx4 v[246:247], v[32:35], off offset:528
	global_load_dwordx4 v[224:227], v[146:147], off
	global_load_dwordx4 v[228:231], v[146:147], off offset:16
	global_load_dwordx4 v[232:235], v[146:147], off offset:512
	global_load_dwordx4 v[236:239], v[146:147], off offset:528
	s_waitcnt vmcnt(8)
	v_fma_f32 v28, v28, v156, v160
	v_fma_f32 v29, v29, v157, v161
	v_fma_f32 v30, v30, v158, v162
	v_fma_f32 v31, v31, v159, v163
	v_fma_f32 v24, v24, v168, v164
	v_fma_f32 v25, v25, v169, v165
	v_fma_f32 v26, v26, v170, v166
	v_fma_f32 v27, v27, v171, v167
	v_fma_f32 v20, v20, v172, v176
	v_fma_f32 v21, v21, v173, v177
	v_fma_f32 v22, v22, v174, v178
	v_fma_f32 v23, v23, v175, v179
	v_fma_f32 v16, v16, v184, v180
	v_fma_f32 v17, v17, v185, v181
	v_fma_f32 v18, v18, v186, v182
	v_fma_f32 v19, v19, v187, v183
	global_store_dwordx4 v[248:249], v[28:31], off
	global_store_dwordx4 v[248:249], v[24:27], off offset:16
	global_store_dwordx4 v[248:249], v[20:23], off offset:512
	global_store_dwordx4 v[248:249], v[16:19], off offset:528
	s_waitcnt vmcnt(4)
	v_fma_f32 v12, v12, v156, v224
	v_fma_f32 v13, v13, v157, v225
	v_fma_f32 v14, v14, v158, v226
	v_fma_f32 v15, v15, v159, v227
	v_fma_f32 v8, v8, v168, v228
	v_fma_f32 v9, v9, v169, v229
	v_fma_f32 v10, v10, v170, v230
	v_fma_f32 v11, v11, v171, v231
	v_fma_f32 v4, v4, v172, v232
	v_fma_f32 v5, v5, v173, v233
	v_fma_f32 v6, v6, v174, v234
	v_fma_f32 v7, v7, v175, v235
	v_fma_f32 v0, v0, v184, v236
	v_fma_f32 v1, v1, v185, v237
	v_fma_f32 v2, v2, v186, v238
	v_fma_f32 v3, v3, v187, v239
	global_store_dwordx4 v[146:147], v[12:15], off
	global_store_dwordx4 v[146:147], v[8:11], off offset:16
	global_store_dwordx4 v[146:147], v[4:7], off offset:512
	global_store_dwordx4 v[146:147], v[0:3], off offset:528
	s_and_b64 vcc, exec, s[0:1]
	s_mov_b64 s[0:1], -1
	s_cbranch_vccnz .LBB0_1191
	s_andn2_b64 vcc, exec, s[8:9]
	s_cbranch_vccnz .LBB0_1190
	s_barrier
	s_branch .LBB0_1190
